# attention row max: cross-half exchange with v_permlane32_swap instead of an LDS bpermute round trip
# speedup vs baseline: 1.0046x; 1.0009x over previous
.LBB0_1267:
	s_or_b64 exec, exec, s[12:13]
	v_max3_f32 v0, v96, s22, v97
	v_max3_f32 v0, v0, v98, v99
	v_max3_f32 v0, v0, v100, v101
	v_max3_f32 v0, v0, v102, v103
	v_max3_f32 v0, v0, v104, v105
	v_max3_f32 v0, v0, v106, v107
	v_max3_f32 v0, v0, v108, v109
	v_max3_f32 v0, v0, v110, v111
	v_max3_f32 v0, v0, v80, v81
	v_max3_f32 v0, v0, v82, v83
	v_max3_f32 v0, v0, v84, v85
	v_max3_f32 v0, v0, v86, v87
	v_max3_f32 v0, v0, v88, v89
	v_max3_f32 v0, v0, v90, v91
	v_max3_f32 v0, v0, v92, v93
	v_max3_f32 v0, v0, v94, v95
	v_mov_b32_e32 v2, v0
	s_nop 1
	v_permlane32_swap_b32_e32 v2, v0
	s_nop 0
	v_max_f32_e32 v2, v2, v2
	v_max_f32_e32 v0, v0, v2
	v_sub_f32_e32 v2, v0, v209
	v_cmp_ge_f32_e32 vcc, s23, v2
	s_cmp_eq_u64 vcc, exec
	s_cbranch_scc1 .LBB0_1260
	v_max_f32_e32 v0, v0, v0
	v_max_f32_e32 v2, v209, v209
	v_max_f32_e32 v2, v2, v0
	v_sub_f32_e32 v0, v209, v2
	v_exp_f32_e32 v0, v0
	v_mov_b32_e32 v209, v2
	v_pk_mul_f32 v[78:79], v[78:79], v[0:1] op_sel_hi:[1,0]
	v_pk_mul_f32 v[76:77], v[76:77], v[0:1] op_sel_hi:[1,0]
	v_pk_mul_f32 v[74:75], v[74:75], v[0:1] op_sel_hi:[1,0]
	v_pk_mul_f32 v[72:73], v[72:73], v[0:1] op_sel_hi:[1,0]
	v_pk_mul_f32 v[70:71], v[70:71], v[0:1] op_sel_hi:[1,0]
	v_pk_mul_f32 v[68:69], v[68:69], v[0:1] op_sel_hi:[1,0]
	v_pk_mul_f32 v[66:67], v[66:67], v[0:1] op_sel_hi:[1,0]
	v_pk_mul_f32 v[64:65], v[64:65], v[0:1] op_sel_hi:[1,0]
	v_pk_mul_f32 v[62:63], v[62:63], v[0:1] op_sel_hi:[1,0]
	v_pk_mul_f32 v[60:61], v[60:61], v[0:1] op_sel_hi:[1,0]
	v_pk_mul_f32 v[58:59], v[58:59], v[0:1] op_sel_hi:[1,0]
	v_pk_mul_f32 v[56:57], v[56:57], v[0:1] op_sel_hi:[1,0]
	v_pk_mul_f32 v[54:55], v[54:55], v[0:1] op_sel_hi:[1,0]
	v_pk_mul_f32 v[52:53], v[52:53], v[0:1] op_sel_hi:[1,0]
	v_pk_mul_f32 v[50:51], v[50:51], v[0:1] op_sel_hi:[1,0]
	v_pk_mul_f32 v[48:49], v[48:49], v[0:1] op_sel_hi:[1,0]
	v_pk_mul_f32 v[46:47], v[46:47], v[0:1] op_sel_hi:[1,0]
	v_pk_mul_f32 v[44:45], v[44:45], v[0:1] op_sel_hi:[1,0]
	v_pk_mul_f32 v[42:43], v[42:43], v[0:1] op_sel_hi:[1,0]
	v_pk_mul_f32 v[40:41], v[40:41], v[0:1] op_sel_hi:[1,0]
	v_pk_mul_f32 v[38:39], v[38:39], v[0:1] op_sel_hi:[1,0]
	v_pk_mul_f32 v[36:37], v[36:37], v[0:1] op_sel_hi:[1,0]
	v_pk_mul_f32 v[34:35], v[34:35], v[0:1] op_sel_hi:[1,0]
	v_pk_mul_f32 v[32:33], v[32:33], v[0:1] op_sel_hi:[1,0]
	v_pk_mul_f32 v[30:31], v[30:31], v[0:1] op_sel_hi:[1,0]
	v_pk_mul_f32 v[28:29], v[28:29], v[0:1] op_sel_hi:[1,0]
	v_pk_mul_f32 v[26:27], v[26:27], v[0:1] op_sel_hi:[1,0]
	v_pk_mul_f32 v[24:25], v[24:25], v[0:1] op_sel_hi:[1,0]
	v_pk_mul_f32 v[22:23], v[22:23], v[0:1] op_sel_hi:[1,0]
	v_pk_mul_f32 v[20:21], v[20:21], v[0:1] op_sel_hi:[1,0]
	v_pk_mul_f32 v[18:19], v[18:19], v[0:1] op_sel_hi:[1,0]
	v_pk_mul_f32 v[16:17], v[16:17], v[0:1] op_sel_hi:[1,0]
	v_mul_f32_e32 v205, v205, v0
	s_branch .LBB0_1260
